# attention: immediately-awaited shfl_xor 16/32 reduction steps (query norm, softmax row max) via in-place permlane swaps instead of ds_bpermute
# baseline (speedup 1.0000x reference)
.LBB0_184:
	s_or_b64 exec, exec, s[4:5]
	v_ashrrev_i32_e32 v41, 5, v41
	v_and_b32_e32 v86, -8, v41
	v_mul_lo_u32 v41, v86, s0
	v_add3_u32 v40, 0, v41, v40
	v_lshlrev_b32_e32 v76, 16, v4
	v_and_b32_e32 v77, 0xffff0000, v4
	ds_write_b16 v40, v8 offset:36864
	ds_write_b16_d16_hi v40, v8 offset:37408
	ds_write_b16 v40, v9 offset:37952
	ds_write_b16_d16_hi v40, v9 offset:38496
	ds_write_b16 v40, v10 offset:39040
	ds_write_b16_d16_hi v40, v10 offset:39584
	ds_write_b16 v40, v11 offset:40128
	ds_write_b16_d16_hi v40, v11 offset:40672
	v_lshlrev_b32_e32 v78, 16, v0
	v_and_b32_e32 v79, 0xffff0000, v0
	v_pk_mul_f32 v[40:41], v[76:77], v[76:77]
	v_and_b32_e32 v72, 0xffff0000, v5
	v_lshlrev_b32_e32 v73, 16, v5
	v_pk_fma_f32 v[40:41], v[78:79], v[78:79], v[40:41]
	v_and_b32_e32 v74, 0xffff0000, v1
	v_lshlrev_b32_e32 v75, 16, v1
	s_waitcnt lgkmcnt(9)
	v_pk_mul_f32 v[42:43], v[72:73], v[72:73]
	v_and_b32_e32 v68, 0xffff0000, v6
	v_pk_fma_f32 v[42:43], v[74:75], v[74:75], v[42:43]
	v_lshlrev_b32_e32 v69, 16, v6
	v_add_f32_e32 v40, v40, v41
	v_and_b32_e32 v70, 0xffff0000, v2
	v_lshlrev_b32_e32 v71, 16, v2
	v_pk_mul_f32 v[44:45], v[68:69], v[68:69]
	v_add_f32_e32 v40, v43, v40
	v_pk_fma_f32 v[44:45], v[70:71], v[70:71], v[44:45]
	v_and_b32_e32 v64, 0xffff0000, v7
	v_lshlrev_b32_e32 v65, 16, v7
	v_add_f32_e32 v40, v42, v40
	v_and_b32_e32 v66, 0xffff0000, v3
	v_lshlrev_b32_e32 v67, 16, v3
	v_pk_mul_f32 v[46:47], v[64:65], v[64:65]
	v_add_f32_e32 v40, v45, v40
	v_pk_fma_f32 v[46:47], v[66:67], v[66:67], v[46:47]
	v_add_f32_e32 v40, v44, v40
	v_add_f32_e32 v40, v47, v40
	v_add_f32_e32 v40, v46, v40
	v_mov_b32_e32 v41, v40
	s_nop 1
	v_permlane16_swap_b32_e32 v40, v41
	s_add_u32 s8, s8, s6
	s_addc_u32 s9, s9, s7
	v_bfe_u32 v186, v158, 4, 2
	s_add_u32 s4, s10, s6
	v_lshlrev_b32_e32 v92, 5, v186
	s_addc_u32 s5, s11, s7
	s_waitcnt lgkmcnt(0)
	v_add_f32_e32 v190, v40, v41
	global_load_dwordx4 v[40:43], v92, s[8:9] offset:16
	global_load_dwordx4 v[56:59], v92, s[8:9]
	global_load_dwordx4 v[44:47], v92, s[4:5] offset:16
	global_load_dwordx4 v[60:63], v92, s[4:5]
	ds_bpermute_b32 v191, v157, v190
	s_andn2_b64 vcc, exec, s[36:37]
	s_waitcnt vmcnt(1)
	v_mul_f32_e32 v40, v40, v44
	s_waitcnt vmcnt(0)
	v_mul_f32_e32 v48, v56, v60
	v_mul_f32_e32 v56, v48, v78
	global_load_dwordx4 v[48:51], v92, s[8:9] offset:144
	global_load_dwordx4 v[88:91], v92, s[8:9] offset:128
	global_load_dwordx4 v[52:55], v92, s[4:5] offset:144
	s_nop 0
	global_load_dwordx4 v[92:95], v92, s[4:5] offset:128
	v_mul_f32_e32 v57, v57, v61
	v_mul_f32_e32 v58, v58, v62
	v_mul_f32_e32 v59, v59, v63
	v_mul_f32_e32 v40, v40, v71
	v_mul_f32_e32 v41, v41, v45
	v_mul_f32_e32 v42, v42, v46
	v_mul_f32_e32 v43, v43, v47
	v_mul_f32_e32 v57, v57, v79
	v_mul_f32_e32 v58, v58, v75
	v_mul_f32_e32 v59, v59, v74
	v_mul_f32_e32 v41, v41, v70
	v_mul_f32_e32 v42, v42, v67
	v_mul_f32_e32 v43, v43, v66
	s_waitcnt vmcnt(1)
	v_mul_f32_e32 v44, v48, v52
	s_waitcnt vmcnt(0)
	v_mul_f32_e32 v60, v88, v92
	v_mul_f32_e32 v61, v89, v93
	v_mul_f32_e32 v62, v90, v94
	v_mul_f32_e32 v63, v91, v95
	v_mul_f32_e32 v45, v49, v53
	v_mul_f32_e32 v46, v50, v54
	v_mul_f32_e32 v47, v51, v55
	v_mul_f32_e32 v60, v60, v76
	v_mul_f32_e32 v61, v61, v77
	v_mul_f32_e32 v62, v62, v73
	v_mul_f32_e32 v63, v63, v72
	v_mul_f32_e32 v44, v44, v69
	v_mul_f32_e32 v45, v45, v68
	v_mul_f32_e32 v46, v46, v65
	v_mul_f32_e32 v47, v47, v64
	v_cvt_pk_bf16_f32 v72, v56, v57
	v_cvt_pk_bf16_f32 v73, v58, v59
	v_cvt_pk_bf16_f32 v74, v40, v41
	v_cndmask_b32_e64 v40, 0, 1, s[36:37]
	v_cvt_pk_bf16_f32 v75, v42, v43
	v_cvt_pk_bf16_f32 v76, v60, v61
	v_cvt_pk_bf16_f32 v77, v62, v63
	v_cvt_pk_bf16_f32 v78, v44, v45
	v_cvt_pk_bf16_f32 v79, v46, v47
	v_cmp_ne_u32_e64 s[4:5], 1, v40
	v_mov_b64_e32 v[42:43], v[38:39]
	v_mov_b64_e32 v[50:51], v[34:35]
	v_mov_b64_e32 v[58:59], v[26:27]
	v_mov_b64_e32 v[66:67], v[18:19]
	v_mov_b64_e32 v[46:47], v[30:31]
	v_mov_b64_e32 v[54:55], v[22:23]
	v_mov_b64_e32 v[62:63], v[14:15]
	v_mov_b64_e32 v[70:71], v[10:11]
	v_mov_b64_e32 v[40:41], v[36:37]
	v_mov_b64_e32 v[48:49], v[32:33]
	v_mov_b64_e32 v[56:57], v[24:25]
	v_mov_b64_e32 v[64:65], v[16:17]
	v_mov_b64_e32 v[44:45], v[28:29]
	v_mov_b64_e32 v[52:53], v[20:21]
	v_mov_b64_e32 v[60:61], v[12:13]
	v_mov_b64_e32 v[68:69], v[8:9]
	s_cbranch_vccnz .LBB0_186
	s_movk_i32 s0, 0x80
	v_lshlrev_b32_e32 v40, 4, v158
	v_cmp_gt_u32_e32 vcc, s0, v81
	v_and_b32_e32 v148, 0x70, v40
	v_add_u32_e32 v40, 0x80, v81
	s_and_b64 vcc, s[40:41], vcc
	v_cndmask_b32_e32 v40, v81, v40, vcc
	v_mul_hi_i32_i24_e32 v41, s38, v40
	v_mul_i32_i24_e32 v40, s38, v40
	v_cmp_gt_i32_e32 vcc, s0, v159
	v_lshl_add_u64 v[68:69], v[40:41], 1, s[42:43]
	v_add_u32_e32 v40, 0x80, v159
	s_and_b64 vcc, vcc, s[40:41]
	v_cndmask_b32_e32 v40, v159, v40, vcc
	v_cmp_gt_i32_e32 vcc, s0, v83
	v_add_u32_e32 v48, 0x80, v83
	s_and_b64 vcc, vcc, s[40:41]
	v_cndmask_b32_e32 v48, v83, v48, vcc
	v_cmp_gt_i32_e32 vcc, s0, v85
	v_add_u32_e32 v56, 0x80, v85
	s_and_b64 vcc, vcc, s[40:41]
	v_cndmask_b32_e32 v56, v85, v56, vcc
	v_cmp_gt_i32_e32 vcc, s0, v87
	v_add_u32_e32 v66, 0x80, v87
	s_and_b64 vcc, vcc, s[40:41]
	v_cndmask_b32_e32 v66, v87, v66, vcc
	v_lshl_add_u64 v[64:65], s[44:45], 0, v[148:149]
	v_mad_i64_i32 v[40:41], s[8:9], s38, v40, 0
	v_ashrrev_i32_e32 v81, 31, v80
	v_mad_i64_i32 v[48:49], s[8:9], s38, v48, 0
	v_ashrrev_i32_e32 v83, 31, v82
	v_mad_i64_i32 v[56:57], s[8:9], s38, v56, 0
	v_ashrrev_i32_e32 v85, 31, v84
	v_mad_i64_i32 v[66:67], s[8:9], s38, v66, 0
	v_ashrrev_i32_e32 v87, 31, v86
	v_lshl_add_u64 v[40:41], v[40:41], 1, v[64:65]
	v_lshl_add_u64 v[44:45], v[80:81], 1, v[68:69]
	v_lshl_add_u64 v[48:49], v[48:49], 1, v[64:65]
	v_lshl_add_u64 v[52:53], v[82:83], 1, v[68:69]
	v_lshl_add_u64 v[56:57], v[56:57], 1, v[64:65]
	v_lshl_add_u64 v[60:61], v[84:85], 1, v[68:69]
	v_lshl_add_u64 v[64:65], v[66:67], 1, v[64:65]
	v_lshl_add_u64 v[68:69], v[86:87], 1, v[68:69]
	global_load_dwordx4 v[40:43], v[40:41], off
	s_nop 0
	global_load_dwordx4 v[44:47], v[44:45], off
	s_nop 0
	global_load_dwordx4 v[48:51], v[48:49], off
	s_nop 0
	global_load_dwordx4 v[52:55], v[52:53], off
	s_nop 0
	global_load_dwordx4 v[56:59], v[56:57], off
	s_nop 0
	global_load_dwordx4 v[60:63], v[60:61], off
	s_nop 0
	global_load_dwordx4 v[64:67], v[64:65], off
	s_nop 0
	global_load_dwordx4 v[68:71], v[68:69], off

.LBB0_188:
	v_add_f32_e32 v84, v190, v191
	v_fmamk_f32 v84, v84, 0x3c800000, v243
	v_cmp_gt_f32_e32 vcc, s88, v84
	v_mul_f32_e32 v85, 0x4b800000, v84
	s_lshr_b32 s26, s50, 2
	v_cndmask_b32_e32 v84, v84, v85, vcc
	v_rsq_f32_e32 v84, v84
	s_lshl_b64 s[4:5], s[26:27], 17
	s_add_u32 s0, s86, s4
	s_addc_u32 s1, s87, s5
	v_mul_f32_e32 v85, 0x45800000, v84
	v_cndmask_b32_e32 v84, v84, v85, vcc
	v_mul_f32_e32 v148, 0x3e000000, v84
	v_lshl_add_u32 v84, v186, 4, 0
	v_add_u32_e32 v204, 0x11800, v84
	ds_read_b128 v[84:87], v204
	s_and_b32 s4, s2, 0xc0
	s_lshl_b32 s4, s4, 1
	v_mul_f32_e32 v193, v148, v96
	v_mul_f32_e32 v194, v148, v97
	s_add_u32 s4, s0, s4
	s_waitcnt lgkmcnt(0)
	v_mul_f32_e32 v96, v193, v84
	v_mul_f32_e32 v97, v194, v85
	s_mov_b32 s0, 0xff61b1e6
	v_mul_f32_e32 v192, v148, v98
	v_mul_f32_e32 v191, v148, v99
	v_max3_f32 v96, v96, s0, v97
	v_mul_f32_e32 v97, v192, v86
	v_mul_f32_e32 v98, v191, v87
	v_max3_f32 v173, v96, v97, v98
	ds_read_b128 v[96:99], v204 offset:64
	v_mul_f32_e32 v190, v148, v100
	v_mul_f32_e32 v203, v148, v101
	v_mul_f32_e32 v201, v148, v102
	v_mul_f32_e32 v200, v148, v103
	s_waitcnt lgkmcnt(0)
	v_mul_f32_e32 v100, v190, v96
	v_mul_f32_e32 v101, v203, v97
	v_max3_f32 v100, v173, v100, v101
	v_mul_f32_e32 v101, v201, v98
	v_mul_f32_e32 v102, v200, v99
	v_max3_f32 v173, v100, v101, v102
	ds_read_b128 v[100:103], v204 offset:128
	v_mul_f32_e32 v197, v148, v104
	v_mul_f32_e32 v199, v148, v105
	v_mul_f32_e32 v198, v148, v106
	v_mul_f32_e32 v196, v148, v107
	s_waitcnt lgkmcnt(0)
	v_mul_f32_e32 v104, v197, v100
	v_mul_f32_e32 v105, v199, v101
	v_max3_f32 v104, v173, v104, v105
	v_mul_f32_e32 v105, v198, v102
	v_mul_f32_e32 v106, v196, v103
	v_max3_f32 v173, v104, v105, v106
	ds_read_b128 v[104:107], v204 offset:192
	v_mul_f32_e32 v195, v148, v108
	v_mul_f32_e32 v212, v148, v109
	v_mul_f32_e32 v210, v148, v110
	v_mul_f32_e32 v209, v148, v111
	s_waitcnt lgkmcnt(0)
	v_mul_f32_e32 v108, v195, v104
	v_mul_f32_e32 v109, v212, v105
	v_max3_f32 v108, v173, v108, v109
	v_mul_f32_e32 v109, v210, v106
	v_mul_f32_e32 v110, v209, v107
	v_max3_f32 v173, v108, v109, v110
	ds_read_b128 v[108:111], v204 offset:256
	v_mul_f32_e32 v206, v148, v112
	v_mul_f32_e32 v208, v148, v113
	v_mul_f32_e32 v207, v148, v114
	v_mul_f32_e32 v205, v148, v115
	s_waitcnt lgkmcnt(0)
	v_mul_f32_e32 v112, v206, v108
	v_mul_f32_e32 v113, v208, v109
	v_max3_f32 v112, v173, v112, v113
	v_mul_f32_e32 v113, v207, v110
	v_mul_f32_e32 v114, v205, v111
	v_max3_f32 v173, v112, v113, v114
	ds_read_b128 v[112:115], v204 offset:320
	v_mul_f32_e32 v202, v148, v124
	v_mul_f32_e32 v220, v148, v125
	v_mul_f32_e32 v218, v148, v126
	v_mul_f32_e32 v217, v148, v127
	s_waitcnt lgkmcnt(0)
	v_mul_f32_e32 v124, v202, v112
	v_mul_f32_e32 v125, v220, v113
	v_max3_f32 v124, v173, v124, v125
	v_mul_f32_e32 v125, v218, v114
	v_mul_f32_e32 v126, v217, v115
	v_max3_f32 v173, v124, v125, v126
	ds_read_b128 v[124:127], v204 offset:384
	v_mul_f32_e32 v214, v148, v128
	v_mul_f32_e32 v216, v148, v129
	v_mul_f32_e32 v215, v148, v130
	v_mul_f32_e32 v213, v148, v131
	s_waitcnt lgkmcnt(0)
	v_mul_f32_e32 v128, v214, v124
	v_mul_f32_e32 v129, v216, v125
	v_max3_f32 v128, v173, v128, v129
	v_mul_f32_e32 v129, v215, v126
	v_mul_f32_e32 v130, v213, v127
	v_max3_f32 v173, v128, v129, v130
	ds_read_b128 v[128:131], v204 offset:448
	v_mul_f32_e32 v211, v148, v132
	v_mul_f32_e32 v228, v148, v133
	v_mul_f32_e32 v226, v148, v134
	v_mul_f32_e32 v225, v148, v135
	s_waitcnt lgkmcnt(0)
	v_mul_f32_e32 v132, v211, v128
	v_mul_f32_e32 v133, v228, v129
	v_max3_f32 v132, v173, v132, v133
	v_mul_f32_e32 v133, v226, v130
	v_mul_f32_e32 v134, v225, v131
	v_max3_f32 v173, v132, v133, v134
	ds_read_b128 v[132:135], v204 offset:512
	v_mul_f32_e32 v222, v148, v136
	v_mul_f32_e32 v224, v148, v137
	v_mul_f32_e32 v223, v148, v138
	v_mul_f32_e32 v221, v148, v139
	s_waitcnt lgkmcnt(0)
	v_mul_f32_e32 v136, v222, v132
	v_mul_f32_e32 v137, v224, v133
	v_max3_f32 v136, v173, v136, v137
	v_mul_f32_e32 v137, v223, v134
	v_mul_f32_e32 v138, v221, v135
	v_max3_f32 v173, v136, v137, v138
	ds_read_b128 v[136:139], v204 offset:576
	v_mul_f32_e32 v219, v148, v140
	v_mul_f32_e32 v239, v148, v141
	v_mul_f32_e32 v237, v148, v142
	v_mul_f32_e32 v236, v148, v143
	s_waitcnt lgkmcnt(0)
	v_mul_f32_e32 v140, v219, v136
	v_mul_f32_e32 v141, v239, v137
	v_max3_f32 v140, v173, v140, v141
	v_mul_f32_e32 v141, v237, v138
	v_mul_f32_e32 v142, v236, v139
	v_max3_f32 v173, v140, v141, v142
	ds_read_b128 v[140:143], v204 offset:640
	v_mul_f32_e32 v231, v148, v144
	v_mul_f32_e32 v234, v148, v145
	v_mul_f32_e32 v233, v148, v146
	v_mul_f32_e32 v230, v148, v147
	s_waitcnt lgkmcnt(0)
	v_mul_f32_e32 v144, v231, v140
	v_mul_f32_e32 v145, v234, v141
	v_max3_f32 v144, v173, v144, v145
	v_mul_f32_e32 v145, v233, v142
	v_mul_f32_e32 v146, v230, v143
	v_max3_f32 v173, v144, v145, v146
	ds_read_b128 v[144:147], v204 offset:704
	v_mul_f32_e32 v227, v148, v120
	v_mul_f32_e32 v250, v148, v121
	v_mul_f32_e32 v249, v148, v122
	v_mul_f32_e32 v248, v148, v123
	s_waitcnt lgkmcnt(0)
	v_mul_f32_e32 v120, v227, v144
	v_mul_f32_e32 v121, v250, v145
	v_max3_f32 v120, v173, v120, v121
	v_mul_f32_e32 v121, v249, v146
	v_mul_f32_e32 v122, v248, v147
	v_max3_f32 v173, v120, v121, v122
	ds_read_b128 v[120:123], v204 offset:768
	v_mov_b32_e32 v176, v243
	v_mul_f32_e32 v243, v148, v116
	v_mul_f32_e32 v246, v148, v117
	v_mul_f32_e32 v244, v148, v118
	s_waitcnt lgkmcnt(0)
	v_mul_f32_e32 v116, v243, v120
	v_mul_f32_e32 v117, v246, v121
	v_mul_f32_e32 v241, v148, v119
	v_max3_f32 v116, v173, v116, v117
	v_mul_f32_e32 v117, v244, v122
	v_mul_f32_e32 v118, v241, v123
	v_max3_f32 v173, v116, v117, v118
	ds_read_b128 v[116:119], v204 offset:832
	v_mul_f32_e32 v238, v148, v92
	v_mul_f32_e32 v177, v148, v93
	v_mul_f32_e32 v253, v148, v94
	v_mul_f32_e32 v252, v148, v95
	s_waitcnt lgkmcnt(0)
	v_mul_f32_e32 v92, v238, v116
	v_mul_f32_e32 v93, v177, v117
	v_max3_f32 v92, v173, v92, v93
	v_mul_f32_e32 v93, v253, v118
	v_mul_f32_e32 v94, v252, v119
	v_max3_f32 v174, v92, v93, v94
	ds_read_b128 v[92:95], v204 offset:896
	v_mul_f32_e32 v251, v148, v88
	v_mul_f32_e32 v173, v148, v89
	v_mul_f32_e32 v183, v148, v90
	v_mul_f32_e32 v175, v148, v91
	s_waitcnt lgkmcnt(0)
	v_mul_f32_e32 v88, v251, v92
	v_mul_f32_e32 v89, v173, v93
	v_max3_f32 v88, v174, v88, v89
	v_mul_f32_e32 v89, v183, v94
	v_mul_f32_e32 v90, v175, v95
	v_max3_f32 v174, v88, v89, v90
	ds_read_b128 v[88:91], v204 offset:960
	v_mul_f32_e32 v80, v148, v80
	v_mul_f32_e32 v184, v148, v81
	s_addc_u32 s5, s1, 0
	s_waitcnt lgkmcnt(0)
	v_mul_f32_e32 v181, v80, v88
	v_mul_f32_e32 v81, v184, v89
	v_max3_f32 v181, v174, v181, v81
	v_mul_f32_e32 v174, v148, v82
	v_mul_f32_e32 v81, v148, v83
	v_mul_f32_e32 v82, v174, v90
	v_mul_f32_e32 v83, v81, v91
	v_max3_f32 v82, v181, v82, v83
	v_mov_b32_e32 v83, v82
	s_nop 1
	v_permlane16_swap_b32_e32 v82, v83
	s_waitcnt lgkmcnt(0)
	v_max_f32_e32 v83, v83, v83
	v_max_f32_e32 v82, v82, v83
	v_mov_b32_e32 v83, v82
	s_nop 1
	v_permlane32_swap_b32_e32 v82, v83
	s_waitcnt lgkmcnt(0)
	v_max_f32_e32 v83, v83, v83
	v_max_f32_e32 v181, v82, v83
	v_fma_f32 v83, v194, v85, -v181
	v_mul_f32_e32 v83, 0x3fb8aa3b, v83
	v_exp_f32_e32 v229, v83
	v_fma_f32 v83, v192, v86, -v181
	v_mul_f32_e32 v83, 0x3fb8aa3b, v83
	v_exp_f32_e32 v232, v83
	v_fma_f32 v83, v191, v87, -v181
	v_mul_f32_e32 v83, 0x3fb8aa3b, v83
	v_exp_f32_e32 v235, v83
	v_fma_f32 v83, v190, v96, -v181
	v_mul_f32_e32 v83, 0x3fb8aa3b, v83
	v_exp_f32_e32 v240, v83
	v_fma_f32 v83, v203, v97, -v181
	v_mul_f32_e32 v83, 0x3fb8aa3b, v83
	v_exp_f32_e32 v242, v83
	v_fma_f32 v83, v201, v98, -v181
	v_mul_f32_e32 v83, 0x3fb8aa3b, v83
	v_exp_f32_e32 v245, v83
	v_fma_f32 v83, v200, v99, -v181
	v_mul_f32_e32 v83, 0x3fb8aa3b, v83
	v_exp_f32_e32 v247, v83
	v_fma_f32 v83, v197, v100, -v181
	v_mul_f32_e32 v83, 0x3fb8aa3b, v83
	v_exp_f32_e32 v191, v83
	v_fma_f32 v83, v199, v101, -v181
	v_mul_f32_e32 v83, 0x3fb8aa3b, v83
	v_fma_f32 v82, v193, v84, -v181
	v_exp_f32_e32 v193, v83
	v_fma_f32 v83, v198, v102, -v181
	v_mul_f32_e32 v83, 0x3fb8aa3b, v83
	v_exp_f32_e32 v197, v83
	v_fma_f32 v83, v196, v103, -v181
	v_mul_f32_e32 v83, 0x3fb8aa3b, v83
	v_exp_f32_e32 v198, v83
	v_fma_f32 v83, v195, v104, -v181
	v_mul_f32_e32 v83, 0x3fb8aa3b, v83
	v_exp_f32_e32 v203, v83
	v_fma_f32 v83, v212, v105, -v181
	v_mul_f32_e32 v83, 0x3fb8aa3b, v83
	v_exp_f32_e32 v212, v83
	v_fma_f32 v83, v210, v106, -v181
	v_mul_f32_e32 v83, 0x3fb8aa3b, v83
	v_exp_f32_e32 v210, v83
	v_fma_f32 v83, v209, v107, -v181
	v_mul_f32_e32 v83, 0x3fb8aa3b, v83
	v_exp_f32_e32 v209, v83
	v_fma_f32 v83, v206, v108, -v181
	v_mul_f32_e32 v83, 0x3fb8aa3b, v83
	v_exp_f32_e32 v148, v83
	v_fma_f32 v83, v208, v109, -v181
	v_mul_f32_e32 v83, 0x3fb8aa3b, v83
	v_exp_f32_e32 v190, v83
	v_fma_f32 v83, v207, v110, -v181
	v_mul_f32_e32 v83, 0x3fb8aa3b, v83
	v_exp_f32_e32 v192, v83
	v_fma_f32 v83, v205, v111, -v181
	v_mul_f32_e32 v83, 0x3fb8aa3b, v83
	v_exp_f32_e32 v194, v83
	v_fma_f32 v83, v202, v112, -v181
	v_mul_f32_e32 v83, 0x3fb8aa3b, v83
	v_exp_f32_e32 v199, v83
	v_fma_f32 v83, v220, v113, -v181
	v_mul_f32_e32 v83, 0x3fb8aa3b, v83
	v_exp_f32_e32 v201, v83
	v_fma_f32 v83, v218, v114, -v181
	v_mul_f32_e32 v83, 0x3fb8aa3b, v83
	v_exp_f32_e32 v205, v83
	v_fma_f32 v83, v217, v115, -v181
	v_mul_f32_e32 v83, 0x3fb8aa3b, v83
	v_exp_f32_e32 v206, v83
	v_fma_f32 v83, v214, v124, -v181
	v_mul_f32_e32 v83, 0x3fb8aa3b, v83
	v_exp_f32_e32 v106, v83
	v_fma_f32 v83, v216, v125, -v181
	v_mul_f32_e32 v83, 0x3fb8aa3b, v83
	v_exp_f32_e32 v110, v83
	v_fma_f32 v83, v215, v126, -v181
	v_mul_f32_e32 v83, 0x3fb8aa3b, v83
	v_exp_f32_e32 v115, v83
	v_fma_f32 v83, v213, v127, -v181
	v_mul_f32_e32 v83, 0x3fb8aa3b, v83
	v_mul_f32_e32 v82, 0x3fb8aa3b, v82
	v_exp_f32_e32 v125, v83
	v_fma_f32 v83, v211, v128, -v181
	v_exp_f32_e32 v204, v82
	v_mul_f32_e32 v83, 0x3fb8aa3b, v83
	v_exp_f32_e32 v195, v83
	v_fma_f32 v83, v228, v129, -v181
	v_mul_f32_e32 v83, 0x3fb8aa3b, v83
	v_exp_f32_e32 v196, v83
	v_fma_f32 v83, v226, v130, -v181
	v_add_f32_e32 v82, 0, v204
	v_mul_f32_e32 v83, 0x3fb8aa3b, v83
	v_add_f32_e32 v82, v229, v82
	v_exp_f32_e32 v200, v83
	v_fma_f32 v83, v225, v131, -v181
	v_add_f32_e32 v82, v232, v82
	v_mul_f32_e32 v83, 0x3fb8aa3b, v83
	v_add_f32_e32 v82, v235, v82
	v_exp_f32_e32 v202, v83
	v_fma_f32 v83, v222, v132, -v181
	v_add_f32_e32 v82, v240, v82
	v_mul_f32_e32 v83, 0x3fb8aa3b, v83
	v_add_f32_e32 v82, v242, v82
	v_exp_f32_e32 v102, v83
	v_fma_f32 v83, v224, v133, -v181
	v_add_f32_e32 v82, v245, v82
	v_mul_f32_e32 v83, 0x3fb8aa3b, v83
	v_add_f32_e32 v82, v247, v82
	v_exp_f32_e32 v104, v83
	v_fma_f32 v83, v223, v134, -v181
	v_add_f32_e32 v82, v191, v82
	v_mul_f32_e32 v83, 0x3fb8aa3b, v83
	v_add_f32_e32 v82, v193, v82
	v_exp_f32_e32 v108, v83
	v_fma_f32 v83, v221, v135, -v181
	v_add_f32_e32 v82, v197, v82
	v_mul_f32_e32 v83, 0x3fb8aa3b, v83
	v_add_f32_e32 v82, v198, v82
	v_exp_f32_e32 v112, v83
	v_fma_f32 v83, v219, v136, -v181
	v_add_f32_e32 v82, v203, v82
	v_mul_f32_e32 v83, 0x3fb8aa3b, v83
	v_add_f32_e32 v82, v212, v82
	v_exp_f32_e32 v126, v83
	v_fma_f32 v83, v239, v137, -v181
	v_add_f32_e32 v82, v210, v82
	v_mul_f32_e32 v83, 0x3fb8aa3b, v83
	v_add_f32_e32 v82, v209, v82
	v_exp_f32_e32 v128, v83
	v_fma_f32 v83, v237, v138, -v181
	v_add_f32_e32 v82, v148, v82
	v_mul_f32_e32 v83, 0x3fb8aa3b, v83
	v_add_f32_e32 v82, v190, v82
	v_exp_f32_e32 v130, v83
	v_fma_f32 v83, v236, v139, -v181
	v_add_f32_e32 v82, v192, v82
	v_mul_f32_e32 v83, 0x3fb8aa3b, v83
	v_add_f32_e32 v82, v194, v82
	v_exp_f32_e32 v131, v83
	v_fma_f32 v83, v231, v140, -v181
	v_add_f32_e32 v82, v199, v82
	v_mul_f32_e32 v83, 0x3fb8aa3b, v83
	v_add_f32_e32 v82, v201, v82
	v_exp_f32_e32 v98, v83
	v_fma_f32 v83, v234, v141, -v181
	v_add_f32_e32 v82, v205, v82
	v_mul_f32_e32 v83, 0x3fb8aa3b, v83
	v_add_f32_e32 v82, v206, v82
	v_exp_f32_e32 v100, v83
	v_fma_f32 v83, v233, v142, -v181
	v_add_f32_e32 v82, v106, v82
	v_mul_f32_e32 v83, 0x3fb8aa3b, v83
	v_add_f32_e32 v82, v110, v82
	v_exp_f32_e32 v103, v83
	v_fma_f32 v83, v230, v143, -v181
	v_add_f32_e32 v82, v115, v82
	v_mul_f32_e32 v83, 0x3fb8aa3b, v83
	v_add_f32_e32 v82, v125, v82
	v_exp_f32_e32 v105, v83
	v_fma_f32 v83, v227, v144, -v181
	v_add_f32_e32 v82, v195, v82
	v_mul_f32_e32 v83, 0x3fb8aa3b, v83
	v_add_f32_e32 v82, v196, v82
	v_exp_f32_e32 v114, v83
	v_fma_f32 v83, v250, v145, -v181
	v_add_f32_e32 v82, v200, v82
	v_mul_f32_e32 v83, 0x3fb8aa3b, v83
	v_add_f32_e32 v82, v202, v82
	v_exp_f32_e32 v124, v83
	v_fma_f32 v83, v249, v146, -v181
	v_add_f32_e32 v82, v102, v82
	v_mul_f32_e32 v83, 0x3fb8aa3b, v83
	v_add_f32_e32 v82, v104, v82
	v_exp_f32_e32 v127, v83
	v_fma_f32 v83, v248, v147, -v181
	v_add_f32_e32 v82, v108, v82
	v_mul_f32_e32 v83, 0x3fb8aa3b, v83
	v_add_f32_e32 v82, v112, v82
	v_exp_f32_e32 v129, v83
	v_fma_f32 v83, v243, v120, -v181
	v_add_f32_e32 v82, v126, v82
	v_mul_f32_e32 v83, 0x3fb8aa3b, v83
	v_add_f32_e32 v82, v128, v82
	v_exp_f32_e32 v96, v83
	v_fma_f32 v83, v246, v121, -v181
	v_add_f32_e32 v82, v130, v82
	v_mul_f32_e32 v83, 0x3fb8aa3b, v83
	v_add_f32_e32 v82, v131, v82
	v_exp_f32_e32 v97, v83
	v_fma_f32 v83, v244, v122, -v181
	v_add_f32_e32 v82, v98, v82
	v_mul_f32_e32 v83, 0x3fb8aa3b, v83
	v_add_f32_e32 v82, v100, v82
	v_exp_f32_e32 v99, v83
	v_fma_f32 v83, v241, v123, -v181
	v_add_f32_e32 v82, v103, v82
	v_mul_f32_e32 v83, 0x3fb8aa3b, v83
	v_add_f32_e32 v82, v105, v82
	v_exp_f32_e32 v101, v83
	v_fma_f32 v83, v238, v116, -v181
	v_add_f32_e32 v82, v114, v82
	v_mul_f32_e32 v83, 0x3fb8aa3b, v83
	v_add_f32_e32 v82, v124, v82
	v_exp_f32_e32 v107, v83
	v_fma_f32 v83, v177, v117, -v181
	v_add_f32_e32 v82, v127, v82
	v_mul_f32_e32 v83, 0x3fb8aa3b, v83
	v_add_f32_e32 v82, v129, v82
	v_exp_f32_e32 v109, v83
	v_fma_f32 v83, v253, v118, -v181
	v_add_f32_e32 v82, v96, v82
	v_mul_f32_e32 v83, 0x3fb8aa3b, v83
	v_add_f32_e32 v82, v97, v82
	v_exp_f32_e32 v111, v83
	v_fma_f32 v83, v252, v119, -v181
	v_add_f32_e32 v82, v99, v82
	v_mul_f32_e32 v83, 0x3fb8aa3b, v83
	v_add_f32_e32 v82, v101, v82
	v_exp_f32_e32 v113, v83
	v_add_f32_e32 v82, v107, v82
	v_add_f32_e32 v82, v109, v82
	v_add_f32_e32 v82, v111, v82
	v_add_f32_e32 v83, v113, v82
	v_fma_f32 v82, v251, v92, -v181
	v_mul_f32_e32 v82, 0x3fb8aa3b, v82
	v_exp_f32_e32 v82, v82
	v_fma_f32 v80, v80, v88, -v181
	v_fma_f32 v88, v174, v90, -v181
	v_mul_u32_u24_e32 v90, 0x220, v187
	v_fma_f32 v81, v81, v91, -v181
	v_add3_u32 v91, 0, v189, v90
	v_add_f32_e32 v84, v82, v83
	v_fma_f32 v83, v173, v93, -v181
	v_add_u32_e32 v93, 0x9000, v91
	v_add_u32_e32 v92, 0xb000, v91
	v_add_u32_e32 v90, 0xd000, v91
	v_add_u32_e32 v91, 0xf000, v91
	v_cvt_pk_bf16_f32 v116, v204, v229
	v_cvt_pk_bf16_f32 v117, v232, v235
	v_cvt_pk_bf16_f32 v118, v240, v242
	v_cvt_pk_bf16_f32 v119, v245, v247
	ds_read2_b64 v[120:123], v93 offset1:4
	ds_read2_b64 v[132:135], v92 offset0:64 offset1:68
	ds_read2_b64 v[136:139], v90 offset0:128 offset1:132
	ds_read2_b64 v[140:143], v91 offset0:192 offset1:196
	s_waitcnt lgkmcnt(3)
	v_mfma_f32_16x16x32_bf16 v[120:123], v[116:119], v[120:123], 0
	v_mul_f32_e32 v83, 0x3fb8aa3b, v83
	v_exp_f32_e32 v83, v83
	v_mul_f32_e32 v80, 0x3fb8aa3b, v80
	s_waitcnt lgkmcnt(2)
	v_mfma_f32_16x16x32_bf16 v[132:135], v[116:119], v[132:135], 0
	v_mul_f32_e32 v88, 0x3fb8aa3b, v88
	v_add_f32_e32 v85, v83, v84
	v_fma_f32 v84, v183, v94, -v181
	s_waitcnt lgkmcnt(1)
	v_mfma_f32_16x16x32_bf16 v[136:139], v[116:119], v[136:139], 0
	v_mul_f32_e32 v84, 0x3fb8aa3b, v84
	v_exp_f32_e32 v84, v84
	v_exp_f32_e32 v88, v88
	s_waitcnt lgkmcnt(0)
	v_mfma_f32_16x16x32_bf16 v[116:119], v[116:119], v[140:143], 0
	v_cvt_pk_bf16_f32 v140, v191, v193
	v_cvt_pk_bf16_f32 v141, v197, v198
	v_cvt_pk_bf16_f32 v142, v203, v212
	v_cvt_pk_bf16_f32 v143, v210, v209
	ds_read2_b64 v[144:147], v93 offset0:8 offset1:12
	s_waitcnt lgkmcnt(0)
	v_mfma_f32_16x16x32_bf16 v[120:123], v[140:143], v[144:147], v[120:123]
	ds_read2_b64 v[144:147], v92 offset0:72 offset1:76
	v_add_f32_e32 v86, v84, v85
	v_fma_f32 v85, v175, v95, -v181
	s_waitcnt lgkmcnt(0)
	v_mfma_f32_16x16x32_bf16 v[132:135], v[140:143], v[144:147], v[132:135]
	ds_read2_b64 v[144:147], v90 offset0:136 offset1:140
	v_mul_f32_e32 v85, 0x3fb8aa3b, v85
	v_exp_f32_e32 v85, v85
	s_waitcnt lgkmcnt(0)
	v_mfma_f32_16x16x32_bf16 v[136:139], v[140:143], v[144:147], v[136:139]
	ds_read2_b64 v[144:147], v91 offset0:200 offset1:204
	v_add_f32_e32 v87, v85, v86
	v_exp_f32_e32 v86, v80
	s_waitcnt lgkmcnt(0)
	v_mfma_f32_16x16x32_bf16 v[116:119], v[140:143], v[144:147], v[116:119]
	v_cvt_pk_bf16_f32 v140, v148, v190
	v_cvt_pk_bf16_f32 v141, v192, v194
	v_cvt_pk_bf16_f32 v142, v199, v201
	v_cvt_pk_bf16_f32 v143, v205, v206
	ds_read2_b64 v[144:147], v93 offset0:16 offset1:20
	s_waitcnt lgkmcnt(0)
	v_mfma_f32_16x16x32_bf16 v[120:123], v[140:143], v[144:147], v[120:123]
	ds_read2_b64 v[144:147], v92 offset0:80 offset1:84
	v_add_f32_e32 v80, v86, v87
	v_fma_f32 v87, v184, v89, -v181
	s_waitcnt lgkmcnt(0)
	v_mfma_f32_16x16x32_bf16 v[132:135], v[140:143], v[144:147], v[132:135]
	ds_read2_b64 v[144:147], v90 offset0:144 offset1:148
	v_mul_f32_e32 v87, 0x3fb8aa3b, v87
	v_exp_f32_e32 v87, v87
	s_waitcnt lgkmcnt(0)
	v_mfma_f32_16x16x32_bf16 v[136:139], v[140:143], v[144:147], v[136:139]
	ds_read2_b64 v[144:147], v91 offset0:208 offset1:212
	v_mul_f32_e32 v81, 0x3fb8aa3b, v81
	v_exp_f32_e32 v89, v81
	s_waitcnt lgkmcnt(0)
	v_mfma_f32_16x16x32_bf16 v[116:119], v[140:143], v[144:147], v[116:119]
	v_cvt_pk_bf16_f32 v140, v106, v110
	v_cvt_pk_bf16_f32 v141, v115, v125
	v_cvt_pk_bf16_f32 v142, v195, v196
	v_cvt_pk_bf16_f32 v143, v200, v202
	ds_read2_b64 v[144:147], v93 offset0:24 offset1:28
	s_waitcnt lgkmcnt(0)
	v_mfma_f32_16x16x32_bf16 v[120:123], v[140:143], v[144:147], v[120:123]
	ds_read2_b64 v[144:147], v92 offset0:88 offset1:92
	v_add_f32_e32 v80, v87, v80
	v_add_f32_e32 v80, v88, v80
	s_waitcnt lgkmcnt(0)
	v_mfma_f32_16x16x32_bf16 v[132:135], v[140:143], v[144:147], v[132:135]
	ds_read2_b64 v[144:147], v90 offset0:152 offset1:156
	v_add_f32_e32 v80, v89, v80
	ds_bpermute_b32 v81, v156, v80
	s_waitcnt lgkmcnt(1)
	v_mfma_f32_16x16x32_bf16 v[136:139], v[140:143], v[144:147], v[136:139]
	ds_read2_b64 v[144:147], v91 offset0:216 offset1:220
	s_waitcnt lgkmcnt(1)
	v_add_f32_e32 v80, v80, v81
	ds_bpermute_b32 v81, v157, v80
	s_waitcnt lgkmcnt(1)
	v_mfma_f32_16x16x32_bf16 v[116:119], v[140:143], v[144:147], v[116:119]
	v_cvt_pk_bf16_f32 v140, v102, v104
	v_cvt_pk_bf16_f32 v141, v108, v112
	v_cvt_pk_bf16_f32 v142, v126, v128
	v_cvt_pk_bf16_f32 v143, v130, v131
	ds_read2_b64 v[144:147], v93 offset0:32 offset1:36
	s_waitcnt lgkmcnt(0)
	v_mfma_f32_16x16x32_bf16 v[120:123], v[140:143], v[144:147], v[120:123]
	ds_read2_b64 v[144:147], v92 offset0:96 offset1:100
	v_add_f32_e32 v80, v80, v81
	v_div_scale_f32 v81, s[8:9], v80, v80, 1.0
	s_waitcnt lgkmcnt(0)
	v_mfma_f32_16x16x32_bf16 v[130:133], v[140:143], v[144:147], v[132:135]
	ds_read2_b64 v[144:147], v90 offset0:160 offset1:164
	v_lshlrev_b32_e32 v148, 1, v187
	v_mov_b32_e32 v243, v176
	s_waitcnt lgkmcnt(0)
	v_mfma_f32_16x16x32_bf16 v[134:137], v[140:143], v[144:147], v[136:139]
	ds_read2_b64 v[144:147], v91 offset0:224 offset1:228
	v_cvt_pk_bf16_f32 v102, v98, v100
	v_cvt_pk_bf16_f32 v103, v103, v105
	v_cvt_pk_bf16_f32 v104, v114, v124
	v_cvt_pk_bf16_f32 v105, v127, v129
	ds_read2_b64 v[124:127], v93 offset0:40 offset1:44
	s_waitcnt lgkmcnt(0)
	v_mfma_f32_16x16x32_bf16 v[120:123], v[102:105], v[124:127], v[120:123]
	ds_read2_b64 v[124:127], v92 offset0:104 offset1:108
	v_mov_b32_e32 v189, 0x1000
	v_mov_b32_e32 v242, v169
	s_waitcnt lgkmcnt(0)
	v_mfma_f32_16x16x32_bf16 v[124:127], v[102:105], v[124:127], v[130:133]
	v_mov_b32_e32 v169, 1
	s_nop 1
	ds_read2_b64 v[128:131], v90 offset0:168 offset1:172
	v_mov_b32_e32 v176, 12
	s_waitcnt lgkmcnt(0)
	v_mfma_f32_16x16x32_bf16 v[128:131], v[102:105], v[128:131], v[134:137]
	s_nop 2
	ds_read2_b64 v[132:135], v91 offset0:232 offset1:236
	v_cvt_pk_bf16_f32 v94, v96, v97
	v_cvt_pk_bf16_f32 v95, v99, v101
	v_mfma_f32_16x16x32_bf16 v[116:119], v[140:143], v[144:147], v[116:119]
	v_cvt_pk_bf16_f32 v96, v107, v109
	v_cvt_pk_bf16_f32 v97, v111, v113
	ds_read2_b64 v[98:101], v93 offset0:48 offset1:52
	s_waitcnt lgkmcnt(1)
	v_mfma_f32_16x16x32_bf16 v[102:105], v[102:105], v[132:135], v[116:119]
	ds_read2_b64 v[106:109], v92 offset0:112 offset1:116
	ds_read2_b64 v[110:113], v90 offset0:176 offset1:180
	v_mov_b32_e32 v244, 0xfffe8000
	s_nop 1
	ds_read2_b64 v[114:117], v91 offset0:240 offset1:244
	v_cvt_pk_bf16_f32 v82, v82, v83
	v_cvt_pk_bf16_f32 v83, v84, v85
	v_cvt_pk_bf16_f32 v84, v86, v87
	v_cvt_pk_bf16_f32 v85, v88, v89
	ds_read2_b64 v[86:89], v93 offset0:56 offset1:60
	s_waitcnt lgkmcnt(4)
	v_mfma_f32_16x16x32_bf16 v[98:101], v[94:97], v[98:101], v[120:123]
	v_mov_b32_e32 v245, 0xffff4000
	v_mov_b32_e32 v246, 0xfffff500
	v_mov_b32_e32 v247, 0x41b17218
	s_waitcnt lgkmcnt(3)
	v_mfma_f32_16x16x32_bf16 v[106:109], v[94:97], v[106:109], v[124:127]
	s_waitcnt lgkmcnt(2)
	v_mfma_f32_16x16x32_bf16 v[110:113], v[94:97], v[110:113], v[128:131]
	s_waitcnt lgkmcnt(1)
	v_mfma_f32_16x16x32_bf16 v[94:97], v[94:97], v[114:117], v[102:105]
	s_waitcnt lgkmcnt(0)
	v_mfma_f32_16x16x32_bf16 v[86:89], v[82:85], v[86:89], v[98:101]
	s_nop 0
	ds_read2_b64 v[102:105], v90 offset0:184 offset1:188
	s_nop 0
	ds_read2_b64 v[98:101], v92 offset0:120 offset1:124
	ds_read2_b64 v[90:93], v91 offset0:248 offset1:252
	s_waitcnt lgkmcnt(1)
	v_mfma_f32_16x16x32_bf16 v[98:101], v[82:85], v[98:101], v[106:109]
	v_mfma_f32_16x16x32_bf16 v[102:105], v[82:85], v[102:105], v[110:113]
	s_waitcnt lgkmcnt(0)
	v_mfma_f32_16x16x32_bf16 v[82:85], v[82:85], v[90:93], v[94:97]
	v_rcp_f32_e32 v90, v81
	s_nop 0
	v_fma_f32 v91, -v81, v90, 1.0
	v_fmac_f32_e32 v90, v91, v90
	v_div_scale_f32 v91, vcc, 1.0, v80, 1.0
	v_mul_f32_e32 v92, v91, v90
	v_fma_f32 v93, -v81, v92, v91
	v_fmac_f32_e32 v92, v93, v90
	v_fma_f32 v81, -v81, v92, v91
	v_div_fmas_f32 v81, v81, v90, v92
	v_div_fixup_f32 v92, v81, v80, 1.0
	v_lshlrev_b32_e32 v81, 2, v186
	v_or_b32_e32 v80, v81, v188
	v_or_b32_e32 v81, v81, v151
	v_lshlrev_b32_e32 v93, 2, v81
	ds_bpermute_b32 v94, v93, v92
	v_ashrrev_i32_e32 v81, 31, v80
	v_lshlrev_b64 v[90:91], 10, v[80:81]
	v_lshl_add_u64 v[90:91], s[4:5], 0, v[90:91]
	v_lshl_add_u64 v[90:91], v[90:91], 0, v[148:149]
	s_waitcnt lgkmcnt(0)
	v_mul_f32_e32 v81, v86, v94
	v_cvt_pk_bf16_f32 v81, v81, v149
	global_store_short v[90:91], v81, off offset:512
	v_mul_f32_e32 v81, v98, v94
	v_cvt_pk_bf16_f32 v81, v81, v149
	global_store_short v[90:91], v81, off offset:544
	v_mul_f32_e32 v81, v102, v94
	v_cvt_pk_bf16_f32 v81, v81, v149
	global_store_short v[90:91], v81, off offset:576
	v_mul_f32_e32 v81, v82, v94
	v_cvt_pk_bf16_f32 v81, v81, v149
	global_store_short v[90:91], v81, off offset:608
	ds_bpermute_b32 v81, v93, v92 offset:4
	v_or_b32_e32 v90, 1, v80
	v_ashrrev_i32_e32 v91, 31, v90
	v_lshlrev_b64 v[90:91], 10, v[90:91]
	v_lshl_add_u64 v[90:91], s[4:5], 0, v[90:91]
	s_waitcnt lgkmcnt(0)
	v_mul_f32_e32 v82, v87, v81
	v_cvt_pk_bf16_f32 v82, v82, v149
	v_lshl_add_u64 v[86:87], v[90:91], 0, v[148:149]
	global_store_short v[86:87], v82, off offset:512
	v_mul_f32_e32 v82, v99, v81
	v_cvt_pk_bf16_f32 v82, v82, v149
	global_store_short v[86:87], v82, off offset:544
	v_mul_f32_e32 v82, v103, v81
	v_mul_f32_e32 v81, v83, v81
	v_cvt_pk_bf16_f32 v82, v82, v149
	global_store_short v[86:87], v82, off offset:576
	v_cvt_pk_bf16_f32 v81, v81, v149
	global_store_short v[86:87], v81, off offset:608
	ds_bpermute_b32 v81, v93, v92 offset:8
	v_or_b32_e32 v82, 2, v80
	v_ashrrev_i32_e32 v83, 31, v82
	v_lshlrev_b64 v[82:83], 10, v[82:83]
	v_lshl_add_u64 v[82:83], s[4:5], 0, v[82:83]
	s_waitcnt lgkmcnt(0)
	v_mul_f32_e32 v86, v88, v81
	v_cvt_pk_bf16_f32 v86, v86, v149
	v_lshl_add_u64 v[82:83], v[82:83], 0, v[148:149]
	global_store_short v[82:83], v86, off offset:512
	v_mul_f32_e32 v86, v100, v81
	v_cvt_pk_bf16_f32 v86, v86, v149
	global_store_short v[82:83], v86, off offset:544
	v_mul_f32_e32 v86, v104, v81
	v_mul_f32_e32 v81, v84, v81
	v_cvt_pk_bf16_f32 v86, v86, v149
	global_store_short v[82:83], v86, off offset:576
	v_cvt_pk_bf16_f32 v81, v81, v149
	global_store_short v[82:83], v81, off offset:608
	ds_bpermute_b32 v82, v93, v92 offset:12
	v_or_b32_e32 v80, 3, v80
	v_ashrrev_i32_e32 v81, 31, v80
	v_lshlrev_b64 v[80:81], 10, v[80:81]
	v_lshl_add_u64 v[80:81], s[4:5], 0, v[80:81]
	s_waitcnt lgkmcnt(0)
	v_mul_f32_e32 v83, v89, v82
	v_cvt_pk_bf16_f32 v83, v83, v149
	v_lshl_add_u64 v[80:81], v[80:81], 0, v[148:149]
	global_store_short v[80:81], v83, off offset:512
	v_mul_f32_e32 v83, v101, v82
	v_cvt_pk_bf16_f32 v83, v83, v149
	global_store_short v[80:81], v83, off offset:544
	v_mul_f32_e32 v83, v105, v82
	v_mul_f32_e32 v82, v85, v82
	s_mov_b64 s[4:5], 0
	v_cvt_pk_bf16_f32 v83, v83, v149
	global_store_short v[80:81], v83, off offset:576
	v_cvt_pk_bf16_f32 v82, v82, v149
	global_store_short v[80:81], v82, off offset:608

.LBB0_202:
	s_or_b64 exec, exec, s[4:5]
	v_lshlrev_b32_e32 v72, 16, v4
	v_and_b32_e32 v73, 0xffff0000, v4
	v_lshlrev_b32_e32 v74, 16, v0
	v_and_b32_e32 v75, 0xffff0000, v0
	v_pk_mul_f32 v[40:41], v[72:73], v[72:73]
	v_and_b32_e32 v68, 0xffff0000, v5
	v_lshlrev_b32_e32 v69, 16, v5
	v_pk_fma_f32 v[40:41], v[74:75], v[74:75], v[40:41]
	v_and_b32_e32 v70, 0xffff0000, v1
	v_lshlrev_b32_e32 v71, 16, v1
	s_waitcnt lgkmcnt(8)
	v_pk_mul_f32 v[42:43], v[68:69], v[68:69]
	v_and_b32_e32 v64, 0xffff0000, v6
	v_pk_fma_f32 v[42:43], v[70:71], v[70:71], v[42:43]
	v_lshlrev_b32_e32 v65, 16, v6
	v_add_f32_e32 v40, v40, v41
	v_and_b32_e32 v66, 0xffff0000, v2
	v_lshlrev_b32_e32 v67, 16, v2
	v_pk_mul_f32 v[44:45], v[64:65], v[64:65]
	v_add_f32_e32 v40, v43, v40
	v_pk_fma_f32 v[44:45], v[66:67], v[66:67], v[44:45]
	v_and_b32_e32 v60, 0xffff0000, v7
	v_lshlrev_b32_e32 v61, 16, v7
	v_add_f32_e32 v40, v42, v40
	v_and_b32_e32 v62, 0xffff0000, v3
	v_lshlrev_b32_e32 v63, 16, v3
	v_pk_mul_f32 v[46:47], v[60:61], v[60:61]
	v_add_f32_e32 v40, v45, v40
	v_pk_fma_f32 v[46:47], v[62:63], v[62:63], v[46:47]
	v_add_f32_e32 v40, v44, v40
	v_add_f32_e32 v40, v47, v40
	v_add_f32_e32 v40, v46, v40
	v_mov_b32_e32 v41, v40
	s_nop 1
	v_permlane16_swap_b32_e32 v40, v41
	v_bfe_u32 v80, v158, 4, 2
	s_add_u32 s4, s86, s12
	s_addc_u32 s5, s87, s13
	v_lshlrev_b32_e32 v81, 5, v80
	s_waitcnt lgkmcnt(0)
	v_add_f32_e32 v89, v40, v41
	global_load_dwordx4 v[40:43], v81, s[4:5] offset:16
	global_load_dwordx4 v[76:79], v81, s[4:5]
	global_load_dwordx4 v[44:47], v81, s[8:9] offset:16
	global_load_dwordx4 v[82:85], v81, s[8:9]
	ds_bpermute_b32 v90, v157, v89
	s_andn2_b64 vcc, exec, s[36:37]
	s_waitcnt vmcnt(1)
	v_mul_f32_e32 v40, v40, v44
	s_waitcnt vmcnt(0)
	v_mul_f32_e32 v48, v76, v82
	v_mul_f32_e32 v74, v48, v74
	global_load_dwordx4 v[48:51], v81, s[4:5] offset:144
	global_load_dwordx4 v[92:95], v81, s[4:5] offset:128
	global_load_dwordx4 v[96:99], v81, s[8:9] offset:144
	global_load_dwordx4 v[100:103], v81, s[8:9] offset:128
	v_mul_f32_e32 v41, v41, v45
	v_mul_f32_e32 v42, v42, v46
	v_mul_f32_e32 v40, v40, v67
	v_mul_f32_e32 v41, v41, v66
	v_mul_f32_e32 v42, v42, v63
	v_mul_f32_e32 v43, v43, v47
	v_mul_f32_e32 v43, v43, v62
	s_waitcnt vmcnt(1)
	v_mul_f32_e32 v44, v48, v96
	s_waitcnt vmcnt(0)
	v_mul_f32_e32 v76, v92, v100
	v_mul_f32_e32 v72, v76, v72
	v_mul_f32_e32 v76, v77, v83
	v_mul_f32_e32 v75, v76, v75
	v_mul_f32_e32 v76, v93, v101
	v_mul_f32_e32 v73, v76, v73
	v_mul_f32_e32 v76, v78, v84
	v_mul_f32_e32 v71, v76, v71
	v_mul_f32_e32 v76, v94, v102
	v_mul_f32_e32 v69, v76, v69
	v_mul_f32_e32 v76, v79, v85
	v_mul_f32_e32 v70, v76, v70
	v_mul_f32_e32 v76, v95, v103
	v_mul_f32_e32 v44, v44, v65
	v_mul_f32_e32 v45, v49, v97
	v_mul_f32_e32 v68, v76, v68
	v_mul_f32_e32 v45, v45, v64
	v_cvt_pk_bf16_f32 v76, v74, v75
	v_cvt_pk_bf16_f32 v77, v71, v70
	v_cvt_pk_bf16_f32 v78, v40, v41
	v_cvt_pk_bf16_f32 v79, v42, v43
	v_cvt_pk_bf16_f32 v40, v72, v73
	v_cvt_pk_bf16_f32 v41, v69, v68
	v_cvt_pk_bf16_f32 v42, v44, v45
	v_cndmask_b32_e64 v44, 0, 1, s[36:37]
	v_mul_f32_e32 v46, v50, v98
	v_mul_f32_e32 v47, v51, v99
	v_cmp_ne_u32_e64 s[4:5], 1, v44
	v_mul_f32_e32 v46, v46, v61
	v_mul_f32_e32 v47, v47, v60
	v_cvt_pk_bf16_f32 v43, v46, v47
	s_cbranch_vccnz .LBB0_204
	s_movk_i32 s0, 0x80
	v_cmp_gt_u32_e32 vcc, s0, v53
	v_add_u32_e32 v10, 0x80, v53
	s_and_b64 vcc, s[40:41], vcc
	v_cndmask_b32_e32 v10, v53, v10, vcc
	v_cmp_gt_i32_e32 vcc, s0, v159
	v_lshlrev_b32_e32 v8, 4, v158
	v_add_u32_e32 v12, 0x80, v159
	s_and_b64 vcc, vcc, s[40:41]
	v_and_b32_e32 v148, 0x70, v8
	v_cndmask_b32_e32 v12, v159, v12, vcc
	v_lshl_add_u64 v[8:9], s[44:45], 0, v[148:149]
	v_mul_hi_i32_i24_e32 v11, s38, v10
	v_mul_i32_i24_e32 v10, s38, v10
	v_mad_i64_i32 v[12:13], s[8:9], s38, v12, 0
	v_lshl_add_u64 v[10:11], v[10:11], 1, s[42:43]
	v_lshl_add_u64 v[12:13], v[12:13], 1, v[8:9]
	v_ashrrev_i32_e32 v53, 31, v52
	global_load_dwordx4 v[36:39], v[12:13], off
	v_lshl_add_u64 v[12:13], v[52:53], 1, v[10:11]
	v_cmp_gt_i32_e32 vcc, s0, v55
	global_load_dwordx4 v[28:31], v[12:13], off
	v_add_u32_e32 v12, 0x80, v55
	s_and_b64 vcc, vcc, s[40:41]
	v_cndmask_b32_e32 v12, v55, v12, vcc
	v_mad_i64_i32 v[12:13], s[8:9], s38, v12, 0
	v_lshl_add_u64 v[12:13], v[12:13], 1, v[8:9]
	v_ashrrev_i32_e32 v55, 31, v54
	global_load_dwordx4 v[32:35], v[12:13], off
	v_lshl_add_u64 v[12:13], v[54:55], 1, v[10:11]
	v_cmp_gt_i32_e32 vcc, s0, v57
	global_load_dwordx4 v[20:23], v[12:13], off
	v_add_u32_e32 v12, 0x80, v57
	s_and_b64 vcc, vcc, s[40:41]
	v_cndmask_b32_e32 v12, v57, v12, vcc
	v_cmp_gt_i32_e32 vcc, s0, v59
	v_add_u32_e32 v16, 0x80, v59
	s_and_b64 vcc, vcc, s[40:41]
	v_cndmask_b32_e32 v16, v59, v16, vcc
	v_mad_i64_i32 v[12:13], s[8:9], s38, v12, 0
	v_mad_i64_i32 v[16:17], s[8:9], s38, v16, 0
	v_lshl_add_u64 v[12:13], v[12:13], 1, v[8:9]
	v_ashrrev_i32_e32 v57, 31, v56
	v_lshl_add_u64 v[8:9], v[16:17], 1, v[8:9]
	v_ashrrev_i32_e32 v59, 31, v58
	global_load_dwordx4 v[24:27], v[12:13], off
	global_load_dwordx4 v[16:19], v[8:9], off
	v_lshl_add_u64 v[12:13], v[56:57], 1, v[10:11]
	v_lshl_add_u64 v[8:9], v[58:59], 1, v[10:11]
	global_load_dwordx4 v[12:15], v[12:13], off
	s_nop 0
	global_load_dwordx4 v[8:11], v[8:9], off

.LBB0_278:
	s_or_b64 exec, exec, s[4:5]
	s_mov_b32 s0, 0xff61b1e6
	v_max3_f32 v40, v79, s0, v78
	v_max3_f32 v40, v40, v90, v89
	v_max3_f32 v40, v40, v91, v75
	v_max3_f32 v40, v40, v69, v68
	v_max3_f32 v40, v40, v71, v70
	v_max3_f32 v40, v40, v65, v64
	v_max3_f32 v40, v40, v67, v66
	v_max3_f32 v40, v40, v61, v60
	v_max3_f32 v40, v40, v63, v62
	v_max3_f32 v40, v40, v57, v56
	v_max3_f32 v40, v40, v59, v58
	v_max3_f32 v40, v40, v53, v52
	v_max3_f32 v40, v40, v55, v54
	v_max3_f32 v40, v40, v49, v48
	v_max3_f32 v40, v40, v51, v50
	v_max3_f32 v40, v40, v45, v44
	v_max3_f32 v40, v40, v47, v46
	v_max3_f32 v40, v40, v94, v41
	v_mov_b32_e32 v42, v40
	s_nop 1
	v_permlane16_swap_b32_e32 v40, v42
	s_sub_i32 s0, 5, s26
	s_ashr_i32 s79, s78, 31
	s_lshl_b32 s1, s11, 7
	s_lshr_b32 s0, s10, s0
	s_waitcnt lgkmcnt(0)
	v_max_f32_e32 v42, v42, v42
	v_max_f32_e32 v40, v40, v42
	v_mov_b32_e32 v42, v40
	s_nop 1
	v_permlane32_swap_b32_e32 v40, v42
	s_lshl_b64 s[4:5], s[78:79], 12
	s_lshl_b32 s1, s1, s26
	s_add_u32 s1, s4, s1
	s_addc_u32 s11, s5, 0
	s_waitcnt lgkmcnt(0)
	v_max_f32_e32 v42, v42, v42
	v_max_f32_e32 v40, v40, v42
	v_sub_f32_e32 v43, v78, v40
	v_mul_f32_e32 v43, 0x3fb8aa3b, v43
	v_exp_f32_e32 v78, v43
	v_sub_f32_e32 v43, v90, v40
	v_mul_f32_e32 v43, 0x3fb8aa3b, v43
	v_exp_f32_e32 v90, v43
	v_sub_f32_e32 v43, v89, v40
	v_mul_f32_e32 v43, 0x3fb8aa3b, v43
	v_exp_f32_e32 v89, v43
	v_sub_f32_e32 v43, v91, v40
	v_mul_f32_e32 v43, 0x3fb8aa3b, v43
	v_exp_f32_e32 v91, v43
	v_sub_f32_e32 v43, v75, v40
	v_mul_f32_e32 v43, 0x3fb8aa3b, v43
	v_exp_f32_e32 v75, v43
	v_sub_f32_e32 v43, v69, v40
	v_mul_f32_e32 v43, 0x3fb8aa3b, v43
	v_exp_f32_e32 v69, v43
	v_sub_f32_e32 v43, v68, v40
	v_mul_f32_e32 v43, 0x3fb8aa3b, v43
	v_exp_f32_e32 v68, v43
	v_sub_f32_e32 v43, v71, v40
	v_mul_f32_e32 v43, 0x3fb8aa3b, v43
	v_exp_f32_e32 v71, v43
	v_sub_f32_e32 v43, v70, v40
	v_mul_f32_e32 v43, 0x3fb8aa3b, v43
	v_exp_f32_e32 v70, v43
	v_sub_f32_e32 v43, v65, v40
	v_mul_f32_e32 v43, 0x3fb8aa3b, v43
	v_exp_f32_e32 v92, v43
	v_sub_f32_e32 v43, v64, v40
	v_mul_f32_e32 v43, 0x3fb8aa3b, v43
	v_exp_f32_e32 v93, v43
	v_sub_f32_e32 v43, v67, v40
	v_mul_f32_e32 v43, 0x3fb8aa3b, v43
	v_exp_f32_e32 v95, v43
	v_sub_f32_e32 v43, v66, v40
	v_mul_f32_e32 v43, 0x3fb8aa3b, v43
	v_exp_f32_e32 v96, v43
	v_sub_f32_e32 v43, v61, v40
	v_mul_f32_e32 v43, 0x3fb8aa3b, v43
	v_exp_f32_e32 v97, v43
	v_sub_f32_e32 v43, v60, v40
	v_mul_f32_e32 v43, 0x3fb8aa3b, v43
	v_exp_f32_e32 v98, v43
	v_sub_f32_e32 v43, v63, v40
	v_mul_f32_e32 v43, 0x3fb8aa3b, v43
	v_exp_f32_e32 v99, v43
	v_sub_f32_e32 v43, v62, v40
	v_mul_f32_e32 v43, 0x3fb8aa3b, v43
	v_exp_f32_e32 v100, v43
	v_sub_f32_e32 v43, v57, v40
	v_mul_f32_e32 v43, 0x3fb8aa3b, v43
	v_exp_f32_e32 v101, v43
	v_sub_f32_e32 v43, v56, v40
	v_mul_f32_e32 v43, 0x3fb8aa3b, v43
	v_exp_f32_e32 v102, v43
	v_sub_f32_e32 v43, v59, v40
	v_mul_f32_e32 v43, 0x3fb8aa3b, v43
	v_exp_f32_e32 v103, v43
	v_sub_f32_e32 v43, v58, v40
	v_mul_f32_e32 v43, 0x3fb8aa3b, v43
	v_exp_f32_e32 v104, v43
	v_sub_f32_e32 v43, v53, v40
	v_mul_f32_e32 v43, 0x3fb8aa3b, v43
	v_exp_f32_e32 v53, v43
	v_sub_f32_e32 v43, v52, v40
	v_mul_f32_e32 v43, 0x3fb8aa3b, v43
	v_exp_f32_e32 v105, v43
	v_sub_f32_e32 v43, v55, v40
	v_mul_f32_e32 v43, 0x3fb8aa3b, v43
	v_exp_f32_e32 v52, v43
	v_sub_f32_e32 v43, v54, v40
	v_mul_f32_e32 v43, 0x3fb8aa3b, v43
	v_exp_f32_e32 v106, v43
	v_sub_f32_e32 v43, v49, v40
	v_mul_f32_e32 v43, 0x3fb8aa3b, v43
	v_exp_f32_e32 v107, v43
	v_sub_f32_e32 v43, v48, v40
	v_sub_f32_e32 v42, v79, v40
	v_mul_f32_e32 v43, 0x3fb8aa3b, v43
	v_mul_f32_e32 v42, 0x3fb8aa3b, v42
	v_exp_f32_e32 v108, v43
	v_sub_f32_e32 v43, v51, v40
	v_exp_f32_e32 v79, v42
	v_mul_f32_e32 v43, 0x3fb8aa3b, v43
	v_exp_f32_e32 v109, v43
	v_sub_f32_e32 v43, v50, v40
	v_mul_f32_e32 v43, 0x3fb8aa3b, v43
	v_exp_f32_e32 v110, v43
	v_sub_f32_e32 v43, v45, v40
	v_add_f32_e32 v42, 0, v79
	v_mul_f32_e32 v43, 0x3fb8aa3b, v43
	v_add_f32_e32 v42, v78, v42
	v_exp_f32_e32 v111, v43
	v_sub_f32_e32 v43, v44, v40
	v_add_f32_e32 v42, v90, v42
	v_mul_f32_e32 v43, 0x3fb8aa3b, v43
	v_add_f32_e32 v42, v89, v42
	v_exp_f32_e32 v112, v43
	v_sub_f32_e32 v43, v47, v40
	v_mul_u32_u24_e32 v47, 0x220, v82
	v_add_f32_e32 v42, v91, v42
	v_sub_f32_e32 v45, v94, v40
	v_add3_u32 v94, 0, v88, v47
	v_min_i32_e32 v47, 14, v87
	v_add_f32_e32 v42, v75, v42
	v_cvt_pk_bf16_f32 v48, v79, v78
	v_cvt_pk_bf16_f32 v49, v90, v89
	v_cvt_pk_bf16_f32 v50, v91, v75
	v_lshlrev_b32_e32 v66, 5, v87
	v_lshlrev_b32_e32 v47, 5, v47
	v_add_u32_e32 v75, 0x2200, v94
	v_add_u32_e32 v78, 0x4400, v94
	v_add_u32_e32 v79, 0x6600, v94
	v_add_f32_e32 v42, v69, v42
	v_add_u32_e32 v54, v94, v66
	v_add_u32_e32 v56, v94, v47
	v_add_u32_e32 v58, v75, v66
	v_add_u32_e32 v60, v75, v47
	v_add_u32_e32 v62, v78, v66
	v_add_u32_e32 v64, v78, v47
	v_add_u32_e32 v66, v79, v66
	v_add_u32_e32 v47, v79, v47
	v_add_f32_e32 v42, v68, v42
	v_cvt_pk_bf16_f32 v51, v69, v68
	ds_read_b64 v[54:55], v54 offset:36864
	ds_read_b64 v[56:57], v56 offset:36896
	ds_read_b64 v[58:59], v58 offset:36864
	ds_read_b64 v[68:69], v47 offset:36896
	ds_read_b64 v[60:61], v60 offset:36896
	ds_read_b64 v[62:63], v62 offset:36864
	ds_read_b64 v[64:65], v64 offset:36896
	ds_read_b64 v[66:67], v66 offset:36864
	v_add_f32_e32 v42, v71, v42
	v_add_f32_e32 v42, v70, v42
	s_waitcnt lgkmcnt(6)
	v_mfma_f32_16x16x32_bf16 v[54:57], v[48:51], v[54:57], 0
	v_min_i32_e32 v47, 14, v86
	v_lshlrev_b32_e32 v47, 5, v47
	v_add_f32_e32 v42, v92, v42
	s_waitcnt lgkmcnt(3)
	v_mfma_f32_16x16x32_bf16 v[58:61], v[48:51], v[58:61], 0
	v_add_f32_e32 v42, v93, v42
	v_add_f32_e32 v42, v95, v42
	v_add_f32_e32 v42, v96, v42
	s_waitcnt lgkmcnt(1)
	v_mfma_f32_16x16x32_bf16 v[62:65], v[48:51], v[62:65], 0
	v_add_f32_e32 v42, v97, v42
	v_add_f32_e32 v42, v98, v42
	v_add_f32_e32 v42, v99, v42
	s_waitcnt lgkmcnt(0)
	v_mfma_f32_16x16x32_bf16 v[48:51], v[48:51], v[66:69], 0
	v_cvt_pk_bf16_f32 v66, v71, v70
	v_lshlrev_b32_e32 v70, 5, v86
	v_add_u32_e32 v71, v94, v70
	v_cvt_pk_bf16_f32 v67, v92, v93
	v_cvt_pk_bf16_f32 v68, v95, v96
	v_cvt_pk_bf16_f32 v69, v97, v98
	ds_read_b64 v[86:87], v71 offset:36864
	v_add_u32_e32 v71, v94, v47
	ds_read_b64 v[88:89], v71 offset:36896
	v_add_u32_e32 v71, v75, v70
	s_waitcnt lgkmcnt(0)
	v_mfma_f32_16x16x32_bf16 v[54:57], v[66:69], v[86:89], v[54:57]
	ds_read_b64 v[86:87], v71 offset:36864
	v_add_u32_e32 v71, v75, v47
	ds_read_b64 v[88:89], v71 offset:36896
	v_add_u32_e32 v71, v78, v70
	s_waitcnt lgkmcnt(0)
	v_mfma_f32_16x16x32_bf16 v[58:61], v[66:69], v[86:89], v[58:61]
	ds_read_b64 v[86:87], v71 offset:36864
	v_add_u32_e32 v71, v78, v47
	ds_read_b64 v[88:89], v71 offset:36896
	v_add_u32_e32 v70, v79, v70
	v_add_u32_e32 v47, v79, v47
	v_add_f32_e32 v42, v100, v42
	s_waitcnt lgkmcnt(0)
	v_mfma_f32_16x16x32_bf16 v[62:65], v[66:69], v[86:89], v[62:65]
	ds_read_b64 v[86:87], v70 offset:36864
	ds_read_b64 v[88:89], v47 offset:36896
	v_add_f32_e32 v42, v101, v42
	v_add_f32_e32 v42, v102, v42
	v_add_f32_e32 v42, v103, v42
	v_add_f32_e32 v42, v104, v42
	v_add_f32_e32 v42, v53, v42
	s_waitcnt lgkmcnt(0)
	v_mfma_f32_16x16x32_bf16 v[48:51], v[66:69], v[86:89], v[48:51]
	v_cvt_pk_bf16_f32 v66, v99, v100
	v_cvt_pk_bf16_f32 v67, v101, v102
	v_cvt_pk_bf16_f32 v68, v103, v104
	v_cvt_pk_bf16_f32 v69, v53, v105
	v_min_i32_e32 v47, 14, v85
	v_lshlrev_b32_e32 v53, 5, v85
	v_lshlrev_b32_e32 v47, 5, v47
	v_add_u32_e32 v70, v94, v53
	ds_read_b64 v[86:87], v70 offset:36864
	v_add_u32_e32 v70, v94, v47
	ds_read_b64 v[88:89], v70 offset:36896
	v_add_u32_e32 v70, v75, v53
	s_waitcnt lgkmcnt(0)
	v_mfma_f32_16x16x32_bf16 v[54:57], v[66:69], v[86:89], v[54:57]
	ds_read_b64 v[86:87], v70 offset:36864
	v_add_u32_e32 v70, v75, v47
	ds_read_b64 v[88:89], v70 offset:36896
	v_add_u32_e32 v70, v78, v53
	s_waitcnt lgkmcnt(0)
	v_mfma_f32_16x16x32_bf16 v[58:61], v[66:69], v[86:89], v[58:61]
	ds_read_b64 v[86:87], v70 offset:36864
	v_add_u32_e32 v70, v78, v47
	ds_read_b64 v[88:89], v70 offset:36896
	v_add_u32_e32 v53, v79, v53
	v_add_u32_e32 v47, v79, v47
	s_waitcnt lgkmcnt(0)
	v_mfma_f32_16x16x32_bf16 v[62:65], v[66:69], v[86:89], v[62:65]
	ds_read_b64 v[86:87], v53 offset:36864
	ds_read_b64 v[88:89], v47 offset:36896
	v_add_f32_e32 v42, v105, v42
	v_min_i32_e32 v47, 14, v84
	v_lshlrev_b32_e32 v70, 5, v84
	v_add_f32_e32 v42, v52, v42
	s_waitcnt lgkmcnt(0)
	v_mfma_f32_16x16x32_bf16 v[48:51], v[66:69], v[86:89], v[48:51]
	v_cvt_pk_bf16_f32 v66, v52, v106
	v_lshlrev_b32_e32 v47, 5, v47
	v_add_u32_e32 v52, v94, v70
	v_cvt_pk_bf16_f32 v67, v107, v108
	v_cvt_pk_bf16_f32 v68, v109, v110
	v_cvt_pk_bf16_f32 v69, v111, v112
	ds_read_b64 v[84:85], v52 offset:36864
	v_add_u32_e32 v52, v94, v47
	ds_read_b64 v[86:87], v52 offset:36896
	s_waitcnt lgkmcnt(0)
	v_mfma_f32_16x16x32_bf16 v[52:55], v[66:69], v[84:87], v[54:57]
	s_nop 2
	v_add_u32_e32 v56, v75, v70
	ds_read_b64 v[84:85], v56 offset:36864
	v_add_u32_e32 v56, v75, v47
	ds_read_b64 v[86:87], v56 offset:36896
	s_waitcnt lgkmcnt(0)
	v_mfma_f32_16x16x32_bf16 v[56:59], v[66:69], v[84:87], v[58:61]
	s_nop 2
	v_add_u32_e32 v60, v78, v70
	ds_read_b64 v[84:85], v60 offset:36864
	v_add_u32_e32 v60, v78, v47
	ds_read_b64 v[86:87], v60 offset:36896
	v_add_f32_e32 v42, v106, v42
	v_add_f32_e32 v42, v107, v42
	v_add_f32_e32 v42, v108, v42
	v_mul_f32_e32 v43, 0x3fb8aa3b, v43
	v_sub_f32_e32 v44, v46, v40
	v_add_f32_e32 v42, v109, v42
	v_exp_f32_e32 v43, v43
	v_mul_f32_e32 v44, 0x3fb8aa3b, v44
	s_waitcnt lgkmcnt(0)
	v_mfma_f32_16x16x32_bf16 v[60:63], v[66:69], v[84:87], v[62:65]
	v_add_u32_e32 v47, v79, v47
	v_add_f32_e32 v42, v110, v42
	v_exp_f32_e32 v44, v44
	v_add_u32_e32 v64, v79, v70
	ds_read_b64 v[84:85], v64 offset:36864
	ds_read_b64 v[86:87], v47 offset:36896
	v_add_f32_e32 v42, v111, v42
	v_mul_f32_e32 v45, 0x3fb8aa3b, v45
	v_sub_f32_e32 v41, v41, v40
	v_add_f32_e32 v42, v112, v42
	v_exp_f32_e32 v45, v45
	v_mul_f32_e32 v41, 0x3fb8aa3b, v41
	v_add_f32_e32 v42, v43, v42
	v_exp_f32_e32 v46, v41
	v_add_f32_e32 v42, v44, v42
	v_cvt_pk_bf16_f32 v44, v43, v44
	v_min_i32_e32 v43, 14, v83
	s_waitcnt lgkmcnt(0)
	v_mfma_f32_16x16x32_bf16 v[48:51], v[66:69], v[84:87], v[48:51]
	v_lshlrev_b32_e32 v68, 5, v83
	v_lshlrev_b32_e32 v43, 5, v43
	v_add_f32_e32 v42, v45, v42
	v_add_u32_e32 v64, v94, v68
	v_add_u32_e32 v66, v94, v43
	v_add_f32_e32 v41, v46, v42
	v_cvt_pk_bf16_f32 v45, v45, v46
	v_cvt_pk_bf16_f32 v46, v149, v149
	v_cvt_pk_bf16_f32 v47, v149, v149
	ds_read_b64 v[64:65], v64 offset:36864
	ds_read_b64 v[66:67], v66 offset:36896
	s_waitcnt lgkmcnt(0)
	v_mfma_f32_16x16x32_bf16 v[52:55], v[44:47], v[64:67], v[52:55]
	v_add_u32_e32 v64, v75, v68
	v_add_u32_e32 v66, v75, v43
	ds_bpermute_b32 v42, v156, v41
	ds_read_b64 v[64:65], v64 offset:36864
	ds_read_b64 v[66:67], v66 offset:36896
	s_waitcnt lgkmcnt(0)
	v_mfma_f32_16x16x32_bf16 v[56:59], v[44:47], v[64:67], v[56:59]
	v_add_f32_e32 v41, v41, v42
	v_add_u32_e32 v64, v78, v68
	v_add_u32_e32 v66, v78, v43
	ds_bpermute_b32 v42, v157, v41
	ds_read_b64 v[64:65], v64 offset:36864
	ds_read_b64 v[66:67], v66 offset:36896
	s_waitcnt lgkmcnt(0)
	v_mfma_f32_16x16x32_bf16 v[60:63], v[44:47], v[64:67], v[60:63]
	v_add_u32_e32 v64, v79, v68
	v_add_u32_e32 v43, v79, v43
	v_add_f32_e32 v41, v41, v42
	ds_read_b64 v[64:65], v64 offset:36864
	ds_read_b64 v[66:67], v43 offset:36896
	v_div_scale_f32 v42, s[30:31], v41, v41, 1.0
	v_rcp_f32_e32 v43, v42
	s_waitcnt lgkmcnt(0)
	v_mfma_f32_16x16x32_bf16 v[44:47], v[44:47], v[64:67], v[48:51]
	s_or_b32 s10, s1, s0
	s_mul_i32 s0, s11, 0x600
	s_nop 0
	v_fma_f32 v48, -v42, v43, 1.0
	v_fmac_f32_e32 v43, v48, v43
	v_div_scale_f32 v48, vcc, 1.0, v41, 1.0
	s_mul_hi_u32 s1, s10, 0x600
	v_mul_f32_e32 v49, v48, v43
	s_add_i32 s1, s1, s0
	s_mul_i32 s0, s10, 0x600
	v_fma_f32 v50, -v42, v49, v48
	s_add_u32 s0, s22, s0
	v_fmac_f32_e32 v49, v50, v43
	s_addc_u32 s1, s23, s1
	s_lshl_b32 s4, s70, 6
	v_fma_f32 v42, -v42, v49, v48
	s_ashr_i32 s5, s4, 31
	v_div_fmas_f32 v42, v42, v43, v49
	s_lshl_b64 s[4:5], s[4:5], 1
	v_div_fixup_f32 v48, v42, v41, 1.0
	v_or_b32_e32 v42, v77, v151
	s_add_u32 s4, s0, s4
	v_lshlrev_b32_e32 v49, 2, v42
	s_addc_u32 s5, s1, s5
	ds_bpermute_b32 v50, v49, v48
	s_and_b64 s[8:9], s[66:67], exec
	s_movk_i32 s0, 0x3000
	s_cselect_b32 s0, 0xc00, s0
	s_and_b64 s[8:9], s[50:51], exec
	s_cselect_b32 s8, 0x300, s0
	v_mad_i64_i32 v[42:43], s[30:31], s8, v76, 0
	v_lshl_add_u64 v[42:43], v[42:43], 1, s[4:5]
	s_waitcnt lgkmcnt(0)
	v_mul_f32_e32 v51, v52, v50
	v_lshlrev_b32_e32 v148, 1, v82
	v_cvt_pk_bf16_f32 v51, v51, v149
	v_lshl_add_u64 v[42:43], v[42:43], 0, v[148:149]
	global_store_short v[42:43], v51, off
	v_mul_f32_e32 v51, v56, v50
	v_cvt_pk_bf16_f32 v51, v51, v149
	global_store_short v[42:43], v51, off offset:32
	v_mul_f32_e32 v51, v60, v50
	v_mul_f32_e32 v44, v44, v50
	v_cvt_pk_bf16_f32 v51, v51, v149
	global_store_short v[42:43], v51, off offset:64
	v_cvt_pk_bf16_f32 v44, v44, v149
	global_store_short v[42:43], v44, off offset:96
	ds_bpermute_b32 v44, v49, v48 offset:4
	v_mad_i64_i32 v[42:43], s[30:31], s8, v72, 0
	v_lshl_add_u64 v[42:43], v[42:43], 1, s[4:5]
	v_lshl_add_u64 v[42:43], v[42:43], 0, v[148:149]
	s_waitcnt lgkmcnt(0)
	v_mul_f32_e32 v50, v53, v44
	v_cvt_pk_bf16_f32 v50, v50, v149
	global_store_short v[42:43], v50, off
	v_mul_f32_e32 v50, v57, v44
	v_cvt_pk_bf16_f32 v50, v50, v149
	global_store_short v[42:43], v50, off offset:32
	v_mul_f32_e32 v50, v61, v44
	v_mul_f32_e32 v44, v45, v44
	v_cvt_pk_bf16_f32 v50, v50, v149
	global_store_short v[42:43], v50, off offset:64
	v_cvt_pk_bf16_f32 v44, v44, v149
	global_store_short v[42:43], v44, off offset:96
	ds_bpermute_b32 v44, v49, v48 offset:8
	v_mad_i64_i32 v[42:43], s[30:31], s8, v73, 0
	v_lshl_add_u64 v[42:43], v[42:43], 1, s[4:5]
	v_lshl_add_u64 v[42:43], v[42:43], 0, v[148:149]
	s_waitcnt lgkmcnt(0)
	v_mul_f32_e32 v45, v54, v44
	v_cvt_pk_bf16_f32 v45, v45, v149
	global_store_short v[42:43], v45, off
	v_mul_f32_e32 v45, v58, v44
	v_cvt_pk_bf16_f32 v45, v45, v149
	global_store_short v[42:43], v45, off offset:32
	v_mul_f32_e32 v45, v62, v44
	v_mul_f32_e32 v44, v46, v44
	v_cvt_pk_bf16_f32 v45, v45, v149
	global_store_short v[42:43], v45, off offset:64
	v_cvt_pk_bf16_f32 v44, v44, v149
	global_store_short v[42:43], v44, off offset:96
	ds_bpermute_b32 v44, v49, v48 offset:12
	v_mad_i64_i32 v[42:43], s[8:9], s8, v74, 0
	v_lshl_add_u64 v[42:43], v[42:43], 1, s[4:5]
	v_lshl_add_u64 v[42:43], v[42:43], 0, v[148:149]
	s_waitcnt lgkmcnt(0)
	v_mul_f32_e32 v45, v55, v44
	v_cvt_pk_bf16_f32 v45, v45, v149
	global_store_short v[42:43], v45, off
	v_mul_f32_e32 v45, v59, v44
	v_cvt_pk_bf16_f32 v45, v45, v149
	global_store_short v[42:43], v45, off offset:32
	v_mul_f32_e32 v45, v63, v44
	v_mul_f32_e32 v44, v47, v44
	v_cmp_eq_u32_e32 vcc, 0, v80
	v_cvt_pk_bf16_f32 v45, v45, v149
	global_store_short v[42:43], v45, off offset:64
	v_cvt_pk_bf16_f32 v44, v44, v149
	global_store_short v[42:43], v44, off offset:96
	s_and_saveexec_b64 s[8:9], vcc
	s_cbranch_execz .LBB0_166
	v_cmp_gt_f32_e32 vcc, s88, v41
	s_mul_i32 s11, s11, 48
	s_mul_hi_u32 s0, s10, 48
	v_cndmask_b32_e64 v42, 0, 32, vcc
	s_add_i32 s0, s0, s11
	s_mul_i32 s10, s10, 48
	v_ldexp_f32 v41, v41, v42
	s_add_u32 s1, s20, s10
	v_log_f32_e32 v41, v41
	s_addc_u32 s0, s21, s0
	s_ashr_i32 s71, s70, 31
	s_lshl_b64 s[4:5], s[70:71], 2
	s_add_u32 s10, s1, s4
	s_addc_u32 s11, s0, s5
	v_mul_f32_e32 v42, 0x3f317217, v41
	s_mov_b32 s1, 0x3f317217
	s_and_b64 s[4:5], s[66:67], exec
	v_fma_f32 v42, v41, s1, -v42
	s_cselect_b32 s0, 48, 0xc0
	s_and_b64 s[4:5], s[50:51], exec
	v_fmac_f32_e32 v42, 0x3377d1cf, v41
	s_mov_b32 s1, 0x7f800000
	v_fmac_f32_e32 v42, 0x3f317217, v41
	v_cmp_lt_f32_e64 s[4:5], |v41|, s1
	s_cselect_b32 s0, 12, s0
	s_nop 0
	v_cndmask_b32_e64 v41, v41, v42, s[4:5]
	v_cndmask_b32_e32 v42, 0, v247, vcc
	v_sub_f32_e32 v41, v41, v42
	v_add_f32_e32 v42, v40, v41
	v_mad_i64_i32 v[40:41], s[4:5], s0, v81, 0
	v_lshl_add_u64 v[40:41], v[40:41], 2, s[10:11]
	global_store_dword v[40:41], v42, off
	s_branch .LBB0_166
